# global attention loop: softmax exponentials consumed in place by the PV converts (removed 16 register-pair copies per k-step), V/K fragments in dead VGPRs
# speedup vs baseline: 1.0102x; 1.0102x over previous
; #define MFMA(a, b, c) __builtin_amdgcn_mfma_f32_32x32x16_bf16((a), (b), (c), 0, 0, 0)
; DI int crow(int reg, int h) { return (reg & 3) + 8 * (reg >> 2) + 4 * h; }
; DI float fexp2(float x) { return __builtin_amdgcn_exp2f(x); }
; DI float mx2(float a, float b) { return __builtin_elementwise_maximum(a, b); }
; DI float hmax(float v) { auto rr = __builtin_amdgcn_permlane32_swap(__float_as_uint(v), __float_as_uint(v), false, false); return mx2(__uint_as_float(rr[0]), __uint_as_float(rr[1])); }
; DI f32x16 fzero() { f32x16 z; for (int i = 0; i < 16; ++i) z[i] = 0.f; return z; }
; DI void attn_core2(const u16* __restrict__ P, size_t tokbase, int kcol, int vcol, int n1, int n2, int xs0, bool win, int tq0,
;                    float m0, float l0, const bf16x8 (&qreg)[2][4], f32x16 (&o)[2][2], float (&lsum)[2], char* lds) {
;     ...
;       f32x16 pt[2]; pt[0] = fzero(); pt[1] = fzero();
; #pragma unroll
;       for (int s = 0; s < 4; ++s) {
;         const int ch = 2 * s + h, key = 32 * ks + r;
;         const bf16x8 kf = *(const bf16x8*)(base + ch * 1024 + ((key ^ ch) * 16));
;         pt[0] = MFMA(kf, qreg[0][s], pt[0]);
;         pt[1] = MFMA(kf, qreg[1][s], pt[1]);
;       }
; #pragma unroll
;       for (int qs = 0; qs < 2; ++qs) {
;         if (domask) {
; #pragma unroll
;           for (int reg = 0; reg < 16; ++reg) {
;             const int d = tq0 + 32 * qs - (kt0 + 32 * ks + crow(reg, h));
;             if (d > 128 || d < -128) pt[qs][reg] = -1e30f;
;           }
;         }
;         float mloc = mx2(pt[qs][0], pt[qs][1]);
; #pragma unroll
;         for (int reg = 2; reg < 16; reg += 2) mloc = mx2(mx2(mloc, pt[qs][reg]), pt[qs][reg + 1]);
;         mloc = hmax(mloc) - m[qs];
;         if (__builtin_amdgcn_ballot_w64(mloc > THR) != 0) {
;           const float d = fmaxf(mloc, 0.f);
;           const float alpha = fexp2(-d);
;           m[qs] += d; l[qs] *= alpha; mz[qs] = false;
; #pragma unroll
;           for (int b = 0; b < 2; ++b)
; #pragma unroll
;             for (int reg = 0; reg < 16; ++reg) o[qs][b][reg] *= alpha;
;         }
.LBB0_127:
	v_add_f32_e32 v0, v63, v222
	v_add_f32_e32 v219, v221, v0
	v_add_f32_e32 v0, v15, v223
	s_mov_b64 s[0:1], 0x172000
	v_add_f32_e32 v220, v220, v0
	s_add_i32 s47, s47, 2
	s_andn2_b64 vcc, exec, s[42:43]
	v_lshl_add_u64 v[178:179], v[178:179], 0, s[0:1]
	s_waitcnt lgkmcnt(0)
	s_barrier
	s_cbranch_vccz .LBB0_180
.LBB0_128:
	v_add_co_u32_e32 v0, vcc, 0xffeeb000, v178
	s_nop 1
	v_addc_co_u32_e32 v1, vcc, -1, v179, vcc
	v_add_co_u32_e32 v2, vcc, 0xfff47000, v178
	global_load_dwordx4 v[162:165], v[0:1], off offset:-2560
	s_nop 0
	v_addc_co_u32_e32 v3, vcc, -1, v179, vcc
	global_load_dwordx4 v[170:173], v[2:3], off offset:-512
	global_load_dwordx4 v[166:169], v[0:1], off offset:-2048
	global_load_dwordx4 v[174:177], v[2:3], off
	ds_read_b128 v[206:209], v187
	ds_read_b128 v[226:229], v188
	ds_read_b128 v[238:241], v189
	ds_read_b128 v[242:245], v214
	s_waitcnt lgkmcnt(3)
	v_mfma_f32_32x32x16_bf16 v[32:47], v[206:209], v[130:133], 0
	v_mfma_f32_32x32x16_bf16 v[16:31], v[206:209], v[146:149], 0
	s_waitcnt lgkmcnt(2)
	v_mfma_f32_32x32x16_bf16 v[32:47], v[226:229], v[134:137], v[32:47]
	v_mfma_f32_32x32x16_bf16 v[16:31], v[226:229], v[150:153], v[16:31]
	s_waitcnt lgkmcnt(1)
	v_mfma_f32_32x32x16_bf16 v[32:47], v[238:241], v[138:141], v[32:47]
	v_mfma_f32_32x32x16_bf16 v[16:31], v[238:241], v[154:157], v[16:31]
	s_waitcnt lgkmcnt(0)
	v_mfma_f32_32x32x16_bf16 v[32:47], v[242:245], v[142:145], v[32:47]
	v_mfma_f32_32x32x16_bf16 v[16:31], v[242:245], v[158:161], v[16:31]
	s_nop 10
	v_maximum3_f32 v0, v32, v33, v33
	v_maximum3_f32 v0, v0, v34, v35
	v_maximum3_f32 v0, v0, v36, v37
	v_maximum3_f32 v0, v0, v38, v39
	v_maximum3_f32 v0, v0, v40, v41
	v_maximum3_f32 v0, v0, v42, v43
	v_maximum3_f32 v0, v0, v44, v45
	v_maximum3_f32 v0, v0, v46, v47
	v_mov_b32_e32 v1, v0
	s_nop 1
	v_permlane32_swap_b32_e32 v0, v1
	v_maximum3_f32 v0, v0, v1, v1
	v_sub_f32_e32 v0, v0, v64
	v_cmp_lt_f32_e32 vcc, s76, v0
	s_cbranch_vccz .LBB0_130
	v_max_f32_e32 v0, v0, v0
	v_max_f32_e32 v1, 0, v0
	v_exp_f32_e64 v0, -v1
	v_add_f32_e32 v64, v64, v1
	s_mov_b64 s[40:41], 0
	v_mul_f32_e32 v220, v220, v0
	v_pk_mul_f32 v[128:129], v[128:129], v[0:1] op_sel_hi:[1,0]
	v_pk_mul_f32 v[126:127], v[126:127], v[0:1] op_sel_hi:[1,0]
	v_pk_mul_f32 v[124:125], v[124:125], v[0:1] op_sel_hi:[1,0]
	v_pk_mul_f32 v[122:123], v[122:123], v[0:1] op_sel_hi:[1,0]
	v_pk_mul_f32 v[120:121], v[120:121], v[0:1] op_sel_hi:[1,0]
	v_pk_mul_f32 v[118:119], v[118:119], v[0:1] op_sel_hi:[1,0]
	v_pk_mul_f32 v[116:117], v[116:117], v[0:1] op_sel_hi:[1,0]
	v_pk_mul_f32 v[114:115], v[114:115], v[0:1] op_sel_hi:[1,0]
	v_pk_mul_f32 v[112:113], v[112:113], v[0:1] op_sel_hi:[1,0]
	v_pk_mul_f32 v[110:111], v[110:111], v[0:1] op_sel_hi:[1,0]
	v_pk_mul_f32 v[108:109], v[108:109], v[0:1] op_sel_hi:[1,0]
	v_pk_mul_f32 v[106:107], v[106:107], v[0:1] op_sel_hi:[1,0]
	v_pk_mul_f32 v[104:105], v[104:105], v[0:1] op_sel_hi:[1,0]
	v_pk_mul_f32 v[102:103], v[102:103], v[0:1] op_sel_hi:[1,0]
	v_pk_mul_f32 v[100:101], v[100:101], v[0:1] op_sel_hi:[1,0]
	v_pk_mul_f32 v[98:99], v[98:99], v[0:1] op_sel_hi:[1,0]

; DI float fexp2(float x) { return __builtin_amdgcn_exp2f(x); }
; DI void attn_core2(const u16* __restrict__ P, size_t tokbase, int kcol, int vcol, int n1, int n2, int xs0, bool win, int tq0,
;                    float m0, float l0, const bf16x8 (&qreg)[2][4], f32x16 (&o)[2][2], float (&lsum)[2], char* lds) {
;     ...
;       f32x16 pt[2]; pt[0] = fzero(); pt[1] = fzero();
; #pragma unroll
;       for (int s = 0; s < 4; ++s) {
;         const int ch = 2 * s + h, key = 32 * ks + r;
;         const bf16x8 kf = *(const bf16x8*)(base + ch * 1024 + ((key ^ ch) * 16));
;         pt[0] = MFMA(kf, qreg[0][s], pt[0]);
;         pt[1] = MFMA(kf, qreg[1][s], pt[1]);
;       }
; #pragma unroll
;       for (int qs = 0; qs < 2; ++qs) {
;         if (domask) {
; #pragma unroll
;           for (int reg = 0; reg < 16; ++reg) {
;             const int d = tq0 + 32 * qs - (kt0 + 32 * ks + crow(reg, h));
;             if (d > 128 || d < -128) pt[qs][reg] = -1e30f;
;           }
;         }
;         float mloc = mx2(pt[qs][0], pt[qs][1]);
; #pragma unroll
;         for (int reg = 2; reg < 16; reg += 2) mloc = mx2(mx2(mloc, pt[qs][reg]), pt[qs][reg + 1]);
;         mloc = hmax(mloc) - m[qs];
;         if (__builtin_amdgcn_ballot_w64(mloc > THR) != 0) {
;           const float d = fmaxf(mloc, 0.f);
;           const float alpha = fexp2(-d);
;           m[qs] += d; l[qs] *= alpha; mz[qs] = false;
; #pragma unroll
;           for (int b = 0; b < 2; ++b)
; #pragma unroll
;             for (int reg = 0; reg < 16; ++reg) o[qs][b][reg] *= alpha;
;         }
;         float la = 0.f;
;         if (mz[qs]) {
; #pragma unroll
;           for (int reg = 0; reg < 16; ++reg) { const float e = fexp2(pt[qs][reg]); pt[qs][reg] = e; la += e; }
;         } else {
; #pragma unroll
;           for (int reg = 0; reg < 16; ++reg) { const float e = fexp2(pt[qs][reg] - m[qs]); pt[qs][reg] = e; la += e; }
;         }
;         l[qs] += la;
;       }
; #pragma unroll
;       for (int s2 = 0; s2 < 2; ++s2) {
;         const bf16x8 pb0 = pack8(pt[0], s2), pb1 = pack8(pt[1], s2);
;         const int s16 = 2 * ks + s2;
; #pragma unroll
;         for (int b = 0; b < 2; ++b) {
;           const char* va = base + KB + b * 4096 + s16 * 1024 + trofs;
;           const bf16x8 vf = cat8(vtr(va), vtr(va + 512));
;           o[0][b] = MFMA(vf, pb0, o[0][b]);
;           o[1][b] = MFMA(vf, pb1, o[1][b]);
;         }
;       }
.LBB0_136:
	v_exp_f32_e32 v15, v15
	s_mov_b64 s[0:1], -1
	s_and_b64 vcc, exec, s[38:39]
	s_cbranch_vccnz .LBB0_138
	v_sub_f32_e32 v32, v16, v186
	v_exp_f32_e32 v206, v32
	v_mov_b64_e32 v[62:63], v[30:31]
	v_mov_b64_e32 v[48:49], v[16:17]
	v_sub_f32_e32 v48, v17, v186
	v_mov_b64_e32 v[50:51], v[18:19]
	v_exp_f32_e32 v49, v48
	v_sub_f32_e32 v48, v18, v186
	v_exp_f32_e32 v50, v48
	v_add_f32_e32 v51, 0, v206
	v_mov_b64_e32 v[54:55], v[22:23]
	v_add_f32_e32 v51, v49, v51
	v_mov_b64_e32 v[52:53], v[20:21]
	v_add_f32_e32 v55, v50, v51
	v_sub_f32_e32 v51, v19, v186
	v_exp_f32_e32 v51, v51
	v_sub_f32_e32 v52, v20, v186
	v_exp_f32_e32 v52, v52
	v_sub_f32_e32 v53, v21, v186
	v_exp_f32_e32 v53, v53
	v_sub_f32_e32 v54, v22, v186
	v_exp_f32_e32 v54, v54
	v_add_f32_e32 v55, v51, v55
	v_add_f32_e32 v55, v52, v55
	v_mov_b64_e32 v[58:59], v[26:27]
	v_add_f32_e32 v55, v53, v55
	v_mov_b64_e32 v[56:57], v[24:25]
	v_add_f32_e32 v59, v54, v55
	v_sub_f32_e32 v55, v23, v186
	v_exp_f32_e32 v55, v55
	v_sub_f32_e32 v56, v24, v186
	v_exp_f32_e32 v56, v56
	v_sub_f32_e32 v57, v25, v186
	v_exp_f32_e32 v57, v57
	v_sub_f32_e32 v58, v26, v186
	v_exp_f32_e32 v58, v58
	v_add_f32_e32 v59, v55, v59
	v_add_f32_e32 v59, v56, v59
	v_add_f32_e32 v59, v57, v59
	v_mov_b64_e32 v[60:61], v[28:29]
	v_add_f32_e32 v63, v58, v59
	v_sub_f32_e32 v59, v27, v186
	v_exp_f32_e32 v59, v59
	v_sub_f32_e32 v60, v28, v186
	v_exp_f32_e32 v60, v60
	v_sub_f32_e32 v61, v29, v186
	v_exp_f32_e32 v61, v61
	v_sub_f32_e32 v62, v30, v186
	v_exp_f32_e32 v62, v62
	v_add_f32_e32 v63, v59, v63
	v_add_f32_e32 v63, v60, v63
	v_add_f32_e32 v63, v61, v63
	v_mov_b32_e32 v48, v206
	v_add_f32_e32 v221, v62, v63
	v_sub_f32_e32 v223, v31, v186
	v_mov_b64_e32 v[16:17], v[48:49]
	v_mov_b64_e32 v[18:19], v[50:51]
	v_mov_b64_e32 v[20:21], v[52:53]
	v_mov_b64_e32 v[22:23], v[54:55]
	v_mov_b64_e32 v[24:25], v[56:57]
	v_mov_b64_e32 v[26:27], v[58:59]
	v_mov_b64_e32 v[28:29], v[60:61]
	v_mov_b64_e32 v[30:31], v[62:63]
	s_mov_b64 s[0:1], 0
.LBB0_138:
	s_andn2_b64 vcc, exec, s[0:1]
	s_cbranch_vccnz .LBB0_140
	v_exp_f32_e32 v16, v16
	v_exp_f32_e32 v17, v17
	v_exp_f32_e32 v18, v18
	v_exp_f32_e32 v19, v19
	v_add_f32_e32 v32, 0, v16
	v_exp_f32_e32 v20, v20
	v_add_f32_e32 v32, v17, v32
	v_exp_f32_e32 v21, v21
	v_add_f32_e32 v32, v18, v32
	v_exp_f32_e32 v22, v22
	v_add_f32_e32 v32, v19, v32
	v_exp_f32_e32 v23, v23
	v_add_f32_e32 v32, v20, v32
	v_exp_f32_e32 v24, v24
	v_add_f32_e32 v32, v21, v32
	v_exp_f32_e32 v25, v25
	v_add_f32_e32 v32, v22, v32
	v_exp_f32_e32 v26, v26
	v_add_f32_e32 v32, v23, v32
	v_exp_f32_e32 v27, v27
	v_add_f32_e32 v32, v24, v32
	v_exp_f32_e32 v28, v28
	v_add_f32_e32 v32, v25, v32
	v_exp_f32_e32 v29, v29
	v_add_f32_e32 v32, v26, v32
	v_exp_f32_e32 v30, v30
	v_add_f32_e32 v32, v27, v32
	v_add_f32_e32 v32, v28, v32
	v_add_f32_e32 v32, v29, v32
	v_add_f32_e32 v221, v30, v32
	v_mov_b32_e32 v223, v31
.LBB0_140:
	ds_read_b64_tr_b16 v[226:227], v185 offset:8192
	ds_read_b64_tr_b16 v[228:229], v185 offset:8704
	ds_read_b64_tr_b16 v[238:239], v185 offset:12288
	ds_read_b64_tr_b16 v[240:241], v185 offset:12800
	ds_read_b64_tr_b16 v[242:243], v185 offset:9216
	ds_read_b64_tr_b16 v[244:245], v185 offset:9728
	ds_read_b64_tr_b16 v[246:247], v185 offset:13312
	ds_read_b64_tr_b16 v[248:249], v185 offset:13824
	ds_read_b128 v[206:209], v215
	v_add_f32_e32 v250, v15, v222
	v_add_f32_e32 v220, v220, v250
	v_cvt_pk_bf16_f32 v0, v0, v1
	v_cvt_pk_bf16_f32 v1, v2, v3
	v_cvt_pk_bf16_f32 v2, v4, v5
	v_cvt_pk_bf16_f32 v3, v6, v7
	v_cvt_pk_bf16_f32 v4, v16, v17
	v_cvt_pk_bf16_f32 v5, v18, v19
	v_cvt_pk_bf16_f32 v6, v20, v21
	v_cvt_pk_bf16_f32 v7, v22, v23
	s_waitcnt lgkmcnt(7)
	v_mfma_f32_32x32x16_bf16 v[114:129], v[226:229], v[0:3], v[114:129]
	v_mfma_f32_32x32x16_bf16 v[82:97], v[226:229], v[4:7], v[82:97]
	s_waitcnt lgkmcnt(5)
	v_mfma_f32_32x32x16_bf16 v[98:113], v[238:241], v[0:3], v[98:113]
	v_cvt_pk_bf16_f32 v0, v8, v9
	v_cvt_pk_bf16_f32 v1, v10, v11
	v_cvt_pk_bf16_f32 v2, v12, v13
	v_cvt_pk_bf16_f32 v3, v14, v15
	v_exp_f32_e32 v15, v223
	v_mfma_f32_32x32x16_bf16 v[66:81], v[238:241], v[4:7], v[66:81]
	v_cvt_pk_bf16_f32 v4, v24, v25
	v_cvt_pk_bf16_f32 v5, v26, v27
	v_cvt_pk_bf16_f32 v6, v28, v29
	v_cvt_pk_bf16_f32 v7, v30, v15
	s_waitcnt lgkmcnt(3)
	v_mfma_f32_32x32x16_bf16 v[114:129], v[242:245], v[0:3], v[114:129]
	v_mfma_f32_32x32x16_bf16 v[82:97], v[242:245], v[4:7], v[82:97]
	s_waitcnt lgkmcnt(1)
	v_mfma_f32_32x32x16_bf16 v[98:113], v[246:249], v[0:3], v[98:113]
	v_mfma_f32_32x32x16_bf16 v[66:81], v[246:249], v[4:7], v[66:81]
	ds_read_b128 v[226:229], v216
	ds_read_b128 v[238:241], v217
	ds_read_b128 v[242:245], v218
	s_waitcnt lgkmcnt(3)
	v_mfma_f32_32x32x16_bf16 v[32:47], v[206:209], v[130:133], 0
	v_mfma_f32_32x32x16_bf16 v[16:31], v[206:209], v[146:149], 0
	s_waitcnt lgkmcnt(2)
	v_mfma_f32_32x32x16_bf16 v[32:47], v[226:229], v[134:137], v[32:47]
	v_mfma_f32_32x32x16_bf16 v[16:31], v[226:229], v[150:153], v[16:31]
	s_waitcnt lgkmcnt(1)
	v_mfma_f32_32x32x16_bf16 v[32:47], v[238:241], v[138:141], v[32:47]
	v_mfma_f32_32x32x16_bf16 v[16:31], v[238:241], v[154:157], v[16:31]
	s_waitcnt lgkmcnt(0)
	v_mfma_f32_32x32x16_bf16 v[32:47], v[242:245], v[142:145], v[32:47]
	v_mfma_f32_32x32x16_bf16 v[16:31], v[242:245], v[158:161], v[16:31]
	s_nop 10
	v_maximum3_f32 v0, v32, v33, v33
	v_maximum3_f32 v0, v0, v34, v35
	v_maximum3_f32 v0, v0, v36, v37
	v_maximum3_f32 v0, v0, v38, v39
	v_maximum3_f32 v0, v0, v40, v41
	v_maximum3_f32 v0, v0, v42, v43
	v_maximum3_f32 v0, v0, v44, v45
	v_maximum3_f32 v0, v0, v46, v47
	v_mov_b32_e32 v1, v0
	s_nop 1
	v_permlane32_swap_b32_e32 v0, v1
	v_maximum3_f32 v0, v0, v1, v1
	v_sub_f32_e32 v0, v0, v64
	v_cmp_lt_f32_e32 vcc, s76, v0
	s_cbranch_vccz .LBB0_142
	v_max_f32_e32 v0, v0, v0
	v_max_f32_e32 v1, 0, v0
	v_exp_f32_e64 v0, -v1
	v_add_f32_e32 v64, v64, v1
	s_mov_b64 s[40:41], 0
	v_mul_f32_e32 v220, v220, v0
	v_pk_mul_f32 v[128:129], v[128:129], v[0:1] op_sel_hi:[1,0]
	v_pk_mul_f32 v[126:127], v[126:127], v[0:1] op_sel_hi:[1,0]
	v_pk_mul_f32 v[124:125], v[124:125], v[0:1] op_sel_hi:[1,0]
	v_pk_mul_f32 v[122:123], v[122:123], v[0:1] op_sel_hi:[1,0]
	v_pk_mul_f32 v[120:121], v[120:121], v[0:1] op_sel_hi:[1,0]
	v_pk_mul_f32 v[118:119], v[118:119], v[0:1] op_sel_hi:[1,0]
	v_pk_mul_f32 v[116:117], v[116:117], v[0:1] op_sel_hi:[1,0]
	v_pk_mul_f32 v[114:115], v[114:115], v[0:1] op_sel_hi:[1,0]
	v_pk_mul_f32 v[112:113], v[112:113], v[0:1] op_sel_hi:[1,0]
	v_pk_mul_f32 v[110:111], v[110:111], v[0:1] op_sel_hi:[1,0]
	v_pk_mul_f32 v[108:109], v[108:109], v[0:1] op_sel_hi:[1,0]
	v_pk_mul_f32 v[106:107], v[106:107], v[0:1] op_sel_hi:[1,0]
	v_pk_mul_f32 v[104:105], v[104:105], v[0:1] op_sel_hi:[1,0]
	v_pk_mul_f32 v[102:103], v[102:103], v[0:1] op_sel_hi:[1,0]
	v_pk_mul_f32 v[100:101], v[100:101], v[0:1] op_sel_hi:[1,0]
	v_pk_mul_f32 v[98:99], v[98:99], v[0:1] op_sel_hi:[1,0]

; DI float fexp2(float x) { return __builtin_amdgcn_exp2f(x); }
; DI void attn_core2(const u16* __restrict__ P, size_t tokbase, int kcol, int vcol, int n1, int n2, int xs0, bool win, int tq0,
;                    float m0, float l0, const bf16x8 (&qreg)[2][4], f32x16 (&o)[2][2], float (&lsum)[2], char* lds) {
;     ...
;         if (__builtin_amdgcn_ballot_w64(mloc > THR) != 0) {
;           const float d = fmaxf(mloc, 0.f);
;           const float alpha = fexp2(-d);
;           m[qs] += d; l[qs] *= alpha; mz[qs] = false;
; #pragma unroll
;           for (int b = 0; b < 2; ++b)
; #pragma unroll
;             for (int reg = 0; reg < 16; ++reg) o[qs][b][reg] *= alpha;
;         }
;         float la = 0.f;
;         if (mz[qs]) {
; #pragma unroll
;           for (int reg = 0; reg < 16; ++reg) { const float e = fexp2(pt[qs][reg]); pt[qs][reg] = e; la += e; }
;         } else {
; #pragma unroll
;           for (int reg = 0; reg < 16; ++reg) { const float e = fexp2(pt[qs][reg] - m[qs]); pt[qs][reg] = e; la += e; }
;         }
;         l[qs] += la;
.LBB0_148:
	v_exp_f32_e32 v15, v48
	s_mov_b64 s[0:1], -1
	s_and_b64 vcc, exec, s[38:39]
	s_cbranch_vccnz .LBB0_150
	v_sub_f32_e32 v32, v16, v186
	v_exp_f32_e32 v206, v32
	v_mov_b64_e32 v[62:63], v[30:31]
	v_mov_b64_e32 v[48:49], v[16:17]
	v_sub_f32_e32 v48, v17, v186
	v_mov_b64_e32 v[50:51], v[18:19]
	v_exp_f32_e32 v49, v48
	v_sub_f32_e32 v48, v18, v186
	v_exp_f32_e32 v50, v48
	v_add_f32_e32 v51, 0, v206
	v_mov_b64_e32 v[54:55], v[22:23]
	v_add_f32_e32 v51, v49, v51
	v_mov_b64_e32 v[52:53], v[20:21]
	v_add_f32_e32 v55, v50, v51
	v_sub_f32_e32 v51, v19, v186
	v_exp_f32_e32 v51, v51
	v_sub_f32_e32 v52, v20, v186
	v_exp_f32_e32 v52, v52
	v_sub_f32_e32 v53, v21, v186
	v_exp_f32_e32 v53, v53
	v_sub_f32_e32 v54, v22, v186
	v_exp_f32_e32 v54, v54
	v_add_f32_e32 v55, v51, v55
	v_add_f32_e32 v55, v52, v55
	v_mov_b64_e32 v[58:59], v[26:27]
	v_add_f32_e32 v55, v53, v55
	v_mov_b64_e32 v[56:57], v[24:25]
	v_add_f32_e32 v59, v54, v55
	v_sub_f32_e32 v55, v23, v186
	v_exp_f32_e32 v55, v55
	v_sub_f32_e32 v56, v24, v186
	v_exp_f32_e32 v56, v56
	v_sub_f32_e32 v57, v25, v186
	v_exp_f32_e32 v57, v57
	v_sub_f32_e32 v58, v26, v186
	v_exp_f32_e32 v58, v58
	v_add_f32_e32 v59, v55, v59
	v_add_f32_e32 v59, v56, v59
	v_add_f32_e32 v59, v57, v59
	v_mov_b64_e32 v[60:61], v[28:29]
	v_add_f32_e32 v63, v58, v59
	v_sub_f32_e32 v59, v27, v186
	v_exp_f32_e32 v59, v59
	v_sub_f32_e32 v60, v28, v186
	v_exp_f32_e32 v60, v60
	v_sub_f32_e32 v61, v29, v186
	v_exp_f32_e32 v61, v61
	v_sub_f32_e32 v62, v30, v186
	v_exp_f32_e32 v62, v62
	v_add_f32_e32 v63, v59, v63
	v_add_f32_e32 v63, v60, v63
	v_add_f32_e32 v63, v61, v63
	v_mov_b32_e32 v48, v206
	v_add_f32_e32 v222, v62, v63
	v_sub_f32_e32 v219, v31, v186
	v_mov_b64_e32 v[16:17], v[48:49]
	v_mov_b64_e32 v[18:19], v[50:51]
	v_mov_b64_e32 v[20:21], v[52:53]
	v_mov_b64_e32 v[22:23], v[54:55]
	v_mov_b64_e32 v[24:25], v[56:57]
	v_mov_b64_e32 v[26:27], v[58:59]
	v_mov_b64_e32 v[28:29], v[60:61]
	v_mov_b64_e32 v[30:31], v[62:63]
	s_mov_b64 s[0:1], 0
.LBB0_150:
	s_andn2_b64 vcc, exec, s[0:1]
	s_cbranch_vccnz .LBB0_152
	v_exp_f32_e32 v16, v16
	v_exp_f32_e32 v17, v17
	v_exp_f32_e32 v18, v18
	v_exp_f32_e32 v19, v19
	v_add_f32_e32 v32, 0, v16
	v_exp_f32_e32 v20, v20
	v_add_f32_e32 v32, v17, v32
	v_exp_f32_e32 v21, v21
	v_add_f32_e32 v32, v18, v32
	v_exp_f32_e32 v22, v22
	v_add_f32_e32 v32, v19, v32
	v_exp_f32_e32 v23, v23
	v_add_f32_e32 v32, v20, v32
	v_exp_f32_e32 v24, v24
	v_add_f32_e32 v32, v21, v32
	v_exp_f32_e32 v25, v25
	v_add_f32_e32 v32, v22, v32
	v_exp_f32_e32 v26, v26
	v_add_f32_e32 v32, v23, v32
	v_exp_f32_e32 v27, v27
	v_add_f32_e32 v32, v24, v32
	v_exp_f32_e32 v28, v28
	v_add_f32_e32 v32, v25, v32
	v_exp_f32_e32 v29, v29
	v_add_f32_e32 v32, v26, v32
	v_exp_f32_e32 v30, v30
	v_add_f32_e32 v32, v27, v32
	v_add_f32_e32 v32, v28, v32
	v_add_f32_e32 v32, v29, v32
	v_add_f32_e32 v222, v30, v32
	v_mov_b32_e32 v219, v31
; DI void attn_core2(const u16* __restrict__ P, size_t tokbase, int kcol, int vcol, int n1, int n2, int xs0, bool win, int tq0,
;                    float m0, float l0, const bf16x8 (&qreg)[2][4], f32x16 (&o)[2][2], float (&lsum)[2], char* lds) {
;     ...
;       f32x16 pt[2]; pt[0] = fzero(); pt[1] = fzero();
; #pragma unroll
;       for (int s = 0; s < 4; ++s) {
;         const int ch = 2 * s + h, key = 32 * ks + r;
;         const bf16x8 kf = *(const bf16x8*)(base + ch * 1024 + ((key ^ ch) * 16));
;         pt[0] = MFMA(kf, qreg[0][s], pt[0]);
;         pt[1] = MFMA(kf, qreg[1][s], pt[1]);
;       }
; #pragma unroll
;       for (int qs = 0; qs < 2; ++qs) {
;         if (domask) {
; #pragma unroll
;           for (int reg = 0; reg < 16; ++reg) {
;             const int d = tq0 + 32 * qs - (kt0 + 32 * ks + crow(reg, h));
;             if (d > 128 || d < -128) pt[qs][reg] = -1e30f;
;           }
;         }
;         float mloc = mx2(pt[qs][0], pt[qs][1]);
; #pragma unroll
;         for (int reg = 2; reg < 16; reg += 2) mloc = mx2(mx2(mloc, pt[qs][reg]), pt[qs][reg + 1]);
;         mloc = hmax(mloc) - m[qs];
;         if (__builtin_amdgcn_ballot_w64(mloc > THR) != 0) {
;           const float d = fmaxf(mloc, 0.f);
;           const float alpha = fexp2(-d);
;           m[qs] += d; l[qs] *= alpha; mz[qs] = false;
; #pragma unroll
;           for (int b = 0; b < 2; ++b)
; #pragma unroll
;             for (int reg = 0; reg < 16; ++reg) o[qs][b][reg] *= alpha;
;         }
;         float la = 0.f;
;         if (mz[qs]) {
; #pragma unroll
;           for (int reg = 0; reg < 16; ++reg) { const float e = fexp2(pt[qs][reg]); pt[qs][reg] = e; la += e; }
;         } else {
; #pragma unroll
;           for (int reg = 0; reg < 16; ++reg) { const float e = fexp2(pt[qs][reg] - m[qs]); pt[qs][reg] = e; la += e; }
;         }
;         l[qs] += la;
;       }
; #pragma unroll
;       for (int s2 = 0; s2 < 2; ++s2) {
;         const bf16x8 pb0 = pack8(pt[0], s2), pb1 = pack8(pt[1], s2);
;         const int s16 = 2 * ks + s2;
; #pragma unroll
;         for (int b = 0; b < 2; ++b) {
;           const char* va = base + KB + b * 4096 + s16 * 1024 + trofs;
;           const bf16x8 vf = cat8(vtr(va), vtr(va + 512));
;           o[0][b] = MFMA(vf, pb0, o[0][b]);
;           o[1][b] = MFMA(vf, pb1, o[1][b]);
;         }
;       }
;     ...
;     A_LOAD(kA, vA, it + 1);
;     compute(lds, it);
.LBB0_152:
	ds_read_b64_tr_b16 v[226:227], v185 offset:10240
	ds_read_b64_tr_b16 v[228:229], v185 offset:10752
	ds_read_b64_tr_b16 v[238:239], v185 offset:14336
	ds_read_b64_tr_b16 v[240:241], v185 offset:14848
	ds_read_b64_tr_b16 v[242:243], v185 offset:11264
	ds_read_b64_tr_b16 v[244:245], v185 offset:11776
	ds_read_b64_tr_b16 v[246:247], v185 offset:15360
	ds_read_b64_tr_b16 v[248:249], v185 offset:15872
	v_cvt_pk_bf16_f32 v0, v0, v1
	v_cvt_pk_bf16_f32 v1, v2, v3
	v_cvt_pk_bf16_f32 v2, v4, v5
	v_cvt_pk_bf16_f32 v3, v6, v7
	v_cvt_pk_bf16_f32 v4, v16, v17
	v_cvt_pk_bf16_f32 v5, v18, v19
	v_cvt_pk_bf16_f32 v6, v20, v21
	v_cvt_pk_bf16_f32 v7, v22, v23
	s_waitcnt lgkmcnt(6)
	v_mfma_f32_32x32x16_bf16 v[114:129], v[226:229], v[0:3], v[114:129]
	v_mfma_f32_32x32x16_bf16 v[82:97], v[226:229], v[4:7], v[82:97]
	s_waitcnt lgkmcnt(4)
	v_mfma_f32_32x32x16_bf16 v[98:113], v[238:241], v[0:3], v[98:113]
	v_cvt_pk_bf16_f32 v0, v8, v9
	v_cvt_pk_bf16_f32 v1, v10, v11
	v_cvt_pk_bf16_f32 v2, v12, v13
	v_cvt_pk_bf16_f32 v3, v14, v15
	v_exp_f32_e32 v63, v219
	s_cmpk_lt_u32 s47, 0x42
	s_cselect_b64 s[44:45], -1, 0
	s_cmpk_gt_u32 s47, 0x41
	s_cselect_b64 s[42:43], -1, 0
	v_add_u32_e32 v219, v183, v184
	s_and_b64 vcc, exec, s[42:43]
	v_mfma_f32_32x32x16_bf16 v[66:81], v[238:241], v[4:7], v[66:81]
	v_cvt_pk_bf16_f32 v4, v24, v25
	v_cvt_pk_bf16_f32 v5, v26, v27
	v_cvt_pk_bf16_f32 v6, v28, v29
	v_cvt_pk_bf16_f32 v7, v30, v63
	s_waitcnt lgkmcnt(2)
	v_mfma_f32_32x32x16_bf16 v[114:129], v[242:245], v[0:3], v[114:129]
	v_mfma_f32_32x32x16_bf16 v[82:97], v[242:245], v[4:7], v[82:97]
	s_waitcnt lgkmcnt(0)
	v_mfma_f32_32x32x16_bf16 v[98:113], v[246:249], v[0:3], v[98:113]
	v_mfma_f32_32x32x16_bf16 v[66:81], v[246:249], v[4:7], v[66:81]
	s_waitcnt vmcnt(3)
	ds_write_b128 v181, v[162:165] offset:16384
	s_waitcnt vmcnt(2)
	ds_write_b128 v182, v[170:173] offset:16384
	s_waitcnt vmcnt(1)
	ds_write_b128 v219, v[166:169] offset:24576
	s_waitcnt vmcnt(0)
	ds_write_b128 v219, v[174:177] offset:26624
	s_waitcnt lgkmcnt(0)
	s_barrier
	s_cbranch_vccnz .LBB0_154
	v_add_co_u32_e32 v0, vcc, 0xfffa4000, v178
	s_nop 1
	v_addc_co_u32_e32 v1, vcc, -1, v179, vcc
	global_load_dwordx4 v[162:165], v[0:1], off offset:-2560
	global_load_dwordx4 v[166:169], v[0:1], off offset:-2048
	global_load_dwordx4 v[170:173], v[178:179], off offset:-512
	global_load_dwordx4 v[174:177], v[178:179], off
.LBB0_154:
	v_add_f32_e32 v0, v15, v223
	v_add_f32_e32 v220, v220, v0
	ds_read_b128 v[206:209], v187 offset:16384
	ds_read_b128 v[226:229], v188 offset:16384
	ds_read_b128 v[238:241], v189 offset:16384
	ds_read_b128 v[242:245], v214 offset:16384
	s_waitcnt lgkmcnt(3)
	v_mfma_f32_32x32x16_bf16 v[32:47], v[206:209], v[130:133], 0
	v_mfma_f32_32x32x16_bf16 v[16:31], v[206:209], v[146:149], 0
	s_waitcnt lgkmcnt(2)
	v_mfma_f32_32x32x16_bf16 v[32:47], v[226:229], v[134:137], v[32:47]
	v_mfma_f32_32x32x16_bf16 v[16:31], v[226:229], v[150:153], v[16:31]
	s_waitcnt lgkmcnt(1)
	v_mfma_f32_32x32x16_bf16 v[32:47], v[238:241], v[138:141], v[32:47]
	v_mfma_f32_32x32x16_bf16 v[16:31], v[238:241], v[154:157], v[16:31]
	s_waitcnt lgkmcnt(0)
	v_mfma_f32_32x32x16_bf16 v[32:47], v[242:245], v[142:145], v[32:47]
	v_mfma_f32_32x32x16_bf16 v[16:31], v[242:245], v[158:161], v[16:31]
	s_nop 10
	v_maximum3_f32 v0, v32, v33, v33
	v_maximum3_f32 v0, v0, v34, v35
	v_maximum3_f32 v0, v0, v36, v37
	v_maximum3_f32 v0, v0, v38, v39
	v_maximum3_f32 v0, v0, v40, v41
	v_maximum3_f32 v0, v0, v42, v43
	v_maximum3_f32 v0, v0, v44, v45
	v_maximum3_f32 v0, v0, v46, v47
	v_mov_b32_e32 v1, v0
	s_nop 1
	v_permlane32_swap_b32_e32 v0, v1
	v_maximum3_f32 v0, v0, v1, v1
	v_sub_f32_e32 v0, v0, v64
	v_cmp_lt_f32_e32 vcc, s76, v0
	s_cbranch_vccz .LBB0_156
	v_max_f32_e32 v0, v0, v0
	v_max_f32_e32 v1, 0, v0
	v_exp_f32_e64 v0, -v1
	v_add_f32_e32 v64, v64, v1
	s_mov_b64 s[40:41], 0
	v_mul_f32_e32 v220, v220, v0
	v_pk_mul_f32 v[128:129], v[128:129], v[0:1] op_sel_hi:[1,0]
	v_pk_mul_f32 v[126:127], v[126:127], v[0:1] op_sel_hi:[1,0]
	v_pk_mul_f32 v[124:125], v[124:125], v[0:1] op_sel_hi:[1,0]
	v_pk_mul_f32 v[122:123], v[122:123], v[0:1] op_sel_hi:[1,0]
	v_pk_mul_f32 v[120:121], v[120:121], v[0:1] op_sel_hi:[1,0]
	v_pk_mul_f32 v[118:119], v[118:119], v[0:1] op_sel_hi:[1,0]
	v_pk_mul_f32 v[116:117], v[116:117], v[0:1] op_sel_hi:[1,0]
	v_pk_mul_f32 v[114:115], v[114:115], v[0:1] op_sel_hi:[1,0]
	v_pk_mul_f32 v[112:113], v[112:113], v[0:1] op_sel_hi:[1,0]
	v_pk_mul_f32 v[110:111], v[110:111], v[0:1] op_sel_hi:[1,0]
	v_pk_mul_f32 v[108:109], v[108:109], v[0:1] op_sel_hi:[1,0]
	v_pk_mul_f32 v[106:107], v[106:107], v[0:1] op_sel_hi:[1,0]
	v_pk_mul_f32 v[104:105], v[104:105], v[0:1] op_sel_hi:[1,0]
	v_pk_mul_f32 v[102:103], v[102:103], v[0:1] op_sel_hi:[1,0]
	v_pk_mul_f32 v[100:101], v[100:101], v[0:1] op_sel_hi:[1,0]
	v_pk_mul_f32 v[98:99], v[98:99], v[0:1] op_sel_hi:[1,0]

; DI float fexp2(float x) { return __builtin_amdgcn_exp2f(x); }
; DI void attn_core2(const u16* __restrict__ P, size_t tokbase, int kcol, int vcol, int n1, int n2, int xs0, bool win, int tq0,
;                    float m0, float l0, const bf16x8 (&qreg)[2][4], f32x16 (&o)[2][2], float (&lsum)[2], char* lds) {
;     ...
;       f32x16 pt[2]; pt[0] = fzero(); pt[1] = fzero();
; #pragma unroll
;       for (int s = 0; s < 4; ++s) {
;         const int ch = 2 * s + h, key = 32 * ks + r;
;         const bf16x8 kf = *(const bf16x8*)(base + ch * 1024 + ((key ^ ch) * 16));
;         pt[0] = MFMA(kf, qreg[0][s], pt[0]);
;         pt[1] = MFMA(kf, qreg[1][s], pt[1]);
;       }
; #pragma unroll
;       for (int qs = 0; qs < 2; ++qs) {
;         if (domask) {
; #pragma unroll
;           for (int reg = 0; reg < 16; ++reg) {
;             const int d = tq0 + 32 * qs - (kt0 + 32 * ks + crow(reg, h));
;             if (d > 128 || d < -128) pt[qs][reg] = -1e30f;
;           }
;         }
;         float mloc = mx2(pt[qs][0], pt[qs][1]);
; #pragma unroll
;         for (int reg = 2; reg < 16; reg += 2) mloc = mx2(mx2(mloc, pt[qs][reg]), pt[qs][reg + 1]);
;         mloc = hmax(mloc) - m[qs];
;         if (__builtin_amdgcn_ballot_w64(mloc > THR) != 0) {
;           const float d = fmaxf(mloc, 0.f);
;           const float alpha = fexp2(-d);
;           m[qs] += d; l[qs] *= alpha; mz[qs] = false;
; #pragma unroll
;           for (int b = 0; b < 2; ++b)
; #pragma unroll
;             for (int reg = 0; reg < 16; ++reg) o[qs][b][reg] *= alpha;
;         }
;         float la = 0.f;
;         if (mz[qs]) {
; #pragma unroll
;           for (int reg = 0; reg < 16; ++reg) { const float e = fexp2(pt[qs][reg]); pt[qs][reg] = e; la += e; }
;         } else {
; #pragma unroll
;           for (int reg = 0; reg < 16; ++reg) { const float e = fexp2(pt[qs][reg] - m[qs]); pt[qs][reg] = e; la += e; }
;         }
;         l[qs] += la;
;       }
; #pragma unroll
;       for (int s2 = 0; s2 < 2; ++s2) {
;         const bf16x8 pb0 = pack8(pt[0], s2), pb1 = pack8(pt[1], s2);
;         const int s16 = 2 * ks + s2;
; #pragma unroll
;         for (int b = 0; b < 2; ++b) {
;           const char* va = base + KB + b * 4096 + s16 * 1024 + trofs;
;           const bf16x8 vf = cat8(vtr(va), vtr(va + 512));
;           o[0][b] = MFMA(vf, pb0, o[0][b]);
;           o[1][b] = MFMA(vf, pb1, o[1][b]);
;         }
;       }
.LBB0_162:
	v_exp_f32_e32 v15, v15
	s_mov_b64 s[0:1], -1
	s_and_b64 vcc, exec, s[38:39]
	s_cbranch_vccnz .LBB0_164
	v_sub_f32_e32 v32, v16, v186
	v_exp_f32_e32 v206, v32
	v_mov_b64_e32 v[62:63], v[30:31]
	v_mov_b64_e32 v[48:49], v[16:17]
	v_sub_f32_e32 v48, v17, v186
	v_mov_b64_e32 v[50:51], v[18:19]
	v_exp_f32_e32 v49, v48
	v_sub_f32_e32 v48, v18, v186
	v_exp_f32_e32 v50, v48
	v_add_f32_e32 v51, 0, v206
	v_mov_b64_e32 v[54:55], v[22:23]
	v_add_f32_e32 v51, v49, v51
	v_mov_b64_e32 v[52:53], v[20:21]
	v_add_f32_e32 v55, v50, v51
	v_sub_f32_e32 v51, v19, v186
	v_exp_f32_e32 v51, v51
	v_sub_f32_e32 v52, v20, v186
	v_exp_f32_e32 v52, v52
	v_sub_f32_e32 v53, v21, v186
	v_exp_f32_e32 v53, v53
	v_sub_f32_e32 v54, v22, v186
	v_exp_f32_e32 v54, v54
	v_add_f32_e32 v55, v51, v55
	v_add_f32_e32 v55, v52, v55
	v_mov_b64_e32 v[58:59], v[26:27]
	v_add_f32_e32 v55, v53, v55
	v_mov_b64_e32 v[56:57], v[24:25]
	v_add_f32_e32 v59, v54, v55
	v_sub_f32_e32 v55, v23, v186
	v_exp_f32_e32 v55, v55
	v_sub_f32_e32 v56, v24, v186
	v_exp_f32_e32 v56, v56
	v_sub_f32_e32 v57, v25, v186
	v_exp_f32_e32 v57, v57
	v_sub_f32_e32 v58, v26, v186
	v_exp_f32_e32 v58, v58
	v_add_f32_e32 v59, v55, v59
	v_add_f32_e32 v59, v56, v59
	v_add_f32_e32 v59, v57, v59
	v_mov_b64_e32 v[60:61], v[28:29]
	v_add_f32_e32 v63, v58, v59
	v_sub_f32_e32 v59, v27, v186
	v_exp_f32_e32 v59, v59
	v_sub_f32_e32 v60, v28, v186
	v_exp_f32_e32 v60, v60
	v_sub_f32_e32 v61, v29, v186
	v_exp_f32_e32 v61, v61
	v_sub_f32_e32 v62, v30, v186
	v_exp_f32_e32 v62, v62
	v_add_f32_e32 v63, v59, v63
	v_add_f32_e32 v63, v60, v63
	v_add_f32_e32 v63, v61, v63
	v_mov_b32_e32 v48, v206
	v_add_f32_e32 v222, v62, v63
	v_sub_f32_e32 v224, v31, v186
	v_mov_b64_e32 v[16:17], v[48:49]
	v_mov_b64_e32 v[18:19], v[50:51]
	v_mov_b64_e32 v[20:21], v[52:53]
	v_mov_b64_e32 v[22:23], v[54:55]
	v_mov_b64_e32 v[24:25], v[56:57]
	v_mov_b64_e32 v[26:27], v[58:59]
	v_mov_b64_e32 v[28:29], v[60:61]
	v_mov_b64_e32 v[30:31], v[62:63]
	s_mov_b64 s[0:1], 0
.LBB0_164:
	s_andn2_b64 vcc, exec, s[0:1]
	s_cbranch_vccnz .LBB0_166
	v_exp_f32_e32 v16, v16
	v_exp_f32_e32 v17, v17
	v_exp_f32_e32 v18, v18
	v_exp_f32_e32 v19, v19
	v_add_f32_e32 v32, 0, v16
	v_exp_f32_e32 v20, v20
	v_add_f32_e32 v32, v17, v32
	v_exp_f32_e32 v21, v21
	v_add_f32_e32 v32, v18, v32
	v_exp_f32_e32 v22, v22
	v_add_f32_e32 v32, v19, v32
	v_exp_f32_e32 v23, v23
	v_add_f32_e32 v32, v20, v32
	v_exp_f32_e32 v24, v24
	v_add_f32_e32 v32, v21, v32
	v_exp_f32_e32 v25, v25
	v_add_f32_e32 v32, v22, v32
	v_exp_f32_e32 v26, v26
	v_add_f32_e32 v32, v23, v32
	v_exp_f32_e32 v27, v27
	v_add_f32_e32 v32, v24, v32
	v_exp_f32_e32 v28, v28
	v_add_f32_e32 v32, v25, v32
	v_exp_f32_e32 v29, v29
	v_add_f32_e32 v32, v26, v32
	v_exp_f32_e32 v30, v30
	v_add_f32_e32 v32, v27, v32
	v_add_f32_e32 v32, v28, v32
	v_add_f32_e32 v32, v29, v32
	v_add_f32_e32 v222, v30, v32
	v_mov_b32_e32 v224, v31
.LBB0_166:
	ds_read_b64_tr_b16 v[226:227], v185 offset:24576
	ds_read_b64_tr_b16 v[228:229], v185 offset:25088
	ds_read_b64_tr_b16 v[238:239], v185 offset:28672
	ds_read_b64_tr_b16 v[240:241], v185 offset:29184
	ds_read_b64_tr_b16 v[242:243], v185 offset:25600
	ds_read_b64_tr_b16 v[244:245], v185 offset:26112
	ds_read_b64_tr_b16 v[246:247], v185 offset:29696
	ds_read_b64_tr_b16 v[248:249], v185 offset:30208
	ds_read_b128 v[206:209], v215 offset:16384
	v_add_f32_e32 v250, v15, v223
	v_add_f32_e32 v220, v220, v250
	v_cvt_pk_bf16_f32 v0, v0, v1
	v_cvt_pk_bf16_f32 v1, v2, v3
	v_cvt_pk_bf16_f32 v2, v4, v5
	v_cvt_pk_bf16_f32 v3, v6, v7
	v_cvt_pk_bf16_f32 v4, v16, v17
	v_cvt_pk_bf16_f32 v5, v18, v19
	v_cvt_pk_bf16_f32 v6, v20, v21
	v_cvt_pk_bf16_f32 v7, v22, v23
	s_waitcnt lgkmcnt(7)
	v_mfma_f32_32x32x16_bf16 v[114:129], v[226:229], v[0:3], v[114:129]
	v_mfma_f32_32x32x16_bf16 v[82:97], v[226:229], v[4:7], v[82:97]
	s_waitcnt lgkmcnt(5)
	v_mfma_f32_32x32x16_bf16 v[98:113], v[238:241], v[0:3], v[98:113]
	v_cvt_pk_bf16_f32 v0, v8, v9
	v_cvt_pk_bf16_f32 v1, v10, v11
	v_cvt_pk_bf16_f32 v2, v12, v13
	v_cvt_pk_bf16_f32 v3, v14, v15
	v_exp_f32_e32 v15, v224
	v_mfma_f32_32x32x16_bf16 v[66:81], v[238:241], v[4:7], v[66:81]
	v_cvt_pk_bf16_f32 v4, v24, v25
	v_cvt_pk_bf16_f32 v5, v26, v27
	v_cvt_pk_bf16_f32 v6, v28, v29
	v_cvt_pk_bf16_f32 v7, v30, v15
	s_waitcnt lgkmcnt(3)
	v_mfma_f32_32x32x16_bf16 v[114:129], v[242:245], v[0:3], v[114:129]
	v_mfma_f32_32x32x16_bf16 v[82:97], v[242:245], v[4:7], v[82:97]
	s_waitcnt lgkmcnt(1)
	v_mfma_f32_32x32x16_bf16 v[98:113], v[246:249], v[0:3], v[98:113]
	v_mfma_f32_32x32x16_bf16 v[66:81], v[246:249], v[4:7], v[66:81]
	ds_read_b128 v[226:229], v216 offset:16384
	ds_read_b128 v[238:241], v217 offset:16384
	ds_read_b128 v[242:245], v218 offset:16384
	s_waitcnt lgkmcnt(3)
	v_mfma_f32_32x32x16_bf16 v[32:47], v[206:209], v[130:133], 0
	v_mfma_f32_32x32x16_bf16 v[16:31], v[206:209], v[146:149], 0
	s_waitcnt lgkmcnt(2)
	v_mfma_f32_32x32x16_bf16 v[32:47], v[226:229], v[134:137], v[32:47]
	v_mfma_f32_32x32x16_bf16 v[16:31], v[226:229], v[150:153], v[16:31]
	s_waitcnt lgkmcnt(1)
	v_mfma_f32_32x32x16_bf16 v[32:47], v[238:241], v[138:141], v[32:47]
	v_mfma_f32_32x32x16_bf16 v[16:31], v[238:241], v[154:157], v[16:31]
	s_waitcnt lgkmcnt(0)
	v_mfma_f32_32x32x16_bf16 v[32:47], v[242:245], v[142:145], v[32:47]
	v_mfma_f32_32x32x16_bf16 v[16:31], v[242:245], v[158:161], v[16:31]
	s_nop 10
	v_maximum3_f32 v0, v32, v33, v33
	v_maximum3_f32 v0, v0, v34, v35
	v_maximum3_f32 v0, v0, v36, v37
	v_maximum3_f32 v0, v0, v38, v39
	v_maximum3_f32 v0, v0, v40, v41
	v_maximum3_f32 v0, v0, v42, v43
	v_maximum3_f32 v0, v0, v44, v45
	v_maximum3_f32 v0, v0, v46, v47
	v_mov_b32_e32 v1, v0
	s_nop 1
	v_permlane32_swap_b32_e32 v0, v1
	v_maximum3_f32 v0, v0, v1, v1
	v_sub_f32_e32 v0, v0, v64
	v_cmp_lt_f32_e32 vcc, s76, v0
	s_cbranch_vccz .LBB0_168
	v_max_f32_e32 v0, v0, v0
	v_max_f32_e32 v1, 0, v0
	v_exp_f32_e64 v0, -v1
	v_add_f32_e32 v64, v64, v1
	s_mov_b64 s[40:41], 0
	v_mul_f32_e32 v220, v220, v0
	v_pk_mul_f32 v[128:129], v[128:129], v[0:1] op_sel_hi:[1,0]
	v_pk_mul_f32 v[126:127], v[126:127], v[0:1] op_sel_hi:[1,0]
	v_pk_mul_f32 v[124:125], v[124:125], v[0:1] op_sel_hi:[1,0]
	v_pk_mul_f32 v[122:123], v[122:123], v[0:1] op_sel_hi:[1,0]
	v_pk_mul_f32 v[120:121], v[120:121], v[0:1] op_sel_hi:[1,0]
	v_pk_mul_f32 v[118:119], v[118:119], v[0:1] op_sel_hi:[1,0]
	v_pk_mul_f32 v[116:117], v[116:117], v[0:1] op_sel_hi:[1,0]
	v_pk_mul_f32 v[114:115], v[114:115], v[0:1] op_sel_hi:[1,0]
	v_pk_mul_f32 v[112:113], v[112:113], v[0:1] op_sel_hi:[1,0]
	v_pk_mul_f32 v[110:111], v[110:111], v[0:1] op_sel_hi:[1,0]
	v_pk_mul_f32 v[108:109], v[108:109], v[0:1] op_sel_hi:[1,0]
	v_pk_mul_f32 v[106:107], v[106:107], v[0:1] op_sel_hi:[1,0]
	v_pk_mul_f32 v[104:105], v[104:105], v[0:1] op_sel_hi:[1,0]
	v_pk_mul_f32 v[102:103], v[102:103], v[0:1] op_sel_hi:[1,0]
	v_pk_mul_f32 v[100:101], v[100:101], v[0:1] op_sel_hi:[1,0]
	v_pk_mul_f32 v[98:99], v[98:99], v[0:1] op_sel_hi:[1,0]

; DI float fexp2(float x) { return __builtin_amdgcn_exp2f(x); }
; DI void attn_core2(const u16* __restrict__ P, size_t tokbase, int kcol, int vcol, int n1, int n2, int xs0, bool win, int tq0,
;                    float m0, float l0, const bf16x8 (&qreg)[2][4], f32x16 (&o)[2][2], float (&lsum)[2], char* lds) {
;     ...
;         float la = 0.f;
;         if (mz[qs]) {
; #pragma unroll
;           for (int reg = 0; reg < 16; ++reg) { const float e = fexp2(pt[qs][reg]); pt[qs][reg] = e; la += e; }
;         } else {
; #pragma unroll
;           for (int reg = 0; reg < 16; ++reg) { const float e = fexp2(pt[qs][reg] - m[qs]); pt[qs][reg] = e; la += e; }
;         }
;         l[qs] += la;
.LBB0_174:
	v_exp_f32_e32 v15, v48
	s_mov_b64 s[0:1], -1
	s_and_b64 vcc, exec, s[38:39]
	s_cbranch_vccnz .LBB0_176
	v_sub_f32_e32 v32, v16, v186
	v_exp_f32_e32 v206, v32
	v_mov_b64_e32 v[62:63], v[30:31]
	v_mov_b64_e32 v[48:49], v[16:17]
	v_sub_f32_e32 v48, v17, v186
	v_mov_b64_e32 v[50:51], v[18:19]
	v_exp_f32_e32 v49, v48
	v_sub_f32_e32 v48, v18, v186
	v_exp_f32_e32 v50, v48
	v_add_f32_e32 v51, 0, v206
	v_mov_b64_e32 v[54:55], v[22:23]
	v_add_f32_e32 v51, v49, v51
	v_mov_b64_e32 v[52:53], v[20:21]
	v_add_f32_e32 v55, v50, v51
	v_sub_f32_e32 v51, v19, v186
	v_exp_f32_e32 v51, v51
	v_sub_f32_e32 v52, v20, v186
	v_exp_f32_e32 v52, v52
	v_sub_f32_e32 v53, v21, v186
	v_exp_f32_e32 v53, v53
	v_sub_f32_e32 v54, v22, v186
	v_exp_f32_e32 v54, v54
	v_add_f32_e32 v55, v51, v55
	v_add_f32_e32 v55, v52, v55
	v_mov_b64_e32 v[58:59], v[26:27]
	v_add_f32_e32 v55, v53, v55
	v_mov_b64_e32 v[56:57], v[24:25]
	v_add_f32_e32 v59, v54, v55
	v_sub_f32_e32 v55, v23, v186
	v_exp_f32_e32 v55, v55
	v_sub_f32_e32 v56, v24, v186
	v_exp_f32_e32 v56, v56
	v_sub_f32_e32 v57, v25, v186
	v_exp_f32_e32 v57, v57
	v_sub_f32_e32 v58, v26, v186
	v_exp_f32_e32 v58, v58
	v_add_f32_e32 v59, v55, v59
	v_add_f32_e32 v59, v56, v59
	v_add_f32_e32 v59, v57, v59
	v_mov_b64_e32 v[60:61], v[28:29]
	v_add_f32_e32 v63, v58, v59
	v_sub_f32_e32 v59, v27, v186
	v_exp_f32_e32 v59, v59
	v_sub_f32_e32 v60, v28, v186
	v_exp_f32_e32 v60, v60
	v_sub_f32_e32 v61, v29, v186
	v_exp_f32_e32 v61, v61
	v_sub_f32_e32 v62, v30, v186
	v_exp_f32_e32 v62, v62
	v_add_f32_e32 v63, v59, v63
	v_add_f32_e32 v63, v60, v63
	v_add_f32_e32 v63, v61, v63
	v_mov_b32_e32 v48, v206
	v_add_f32_e32 v222, v62, v63
	v_sub_f32_e32 v224, v31, v186
	v_mov_b64_e32 v[16:17], v[48:49]
	v_mov_b64_e32 v[18:19], v[50:51]
	v_mov_b64_e32 v[20:21], v[52:53]
	v_mov_b64_e32 v[22:23], v[54:55]
	v_mov_b64_e32 v[24:25], v[56:57]
	v_mov_b64_e32 v[26:27], v[58:59]
	v_mov_b64_e32 v[28:29], v[60:61]
	v_mov_b64_e32 v[30:31], v[62:63]
	s_mov_b64 s[0:1], 0

; #define MFMA(a, b, c) __builtin_amdgcn_mfma_f32_32x32x16_bf16((a), (b), (c), 0, 0, 0)
; DI s16x4 vtr(const char* p) { return __builtin_bit_cast(s16x4, __builtin_amdgcn_ds_read_tr16_b64_v4i16((__attribute__((address_space(3))) v4i16_t*)(lds_cptr)p)); }
; DI bf16x8 cat8(s16x4 lo, s16x4 hi) { return __builtin_shufflevector(lo, hi, 0, 1, 2, 3, 4, 5, 6, 7); }
; DI void attn_core2(const u16* __restrict__ P, size_t tokbase, int kcol, int vcol, int n1, int n2, int xs0, bool win, int tq0,
;                    float m0, float l0, const bf16x8 (&qreg)[2][4], f32x16 (&o)[2][2], float (&lsum)[2], char* lds) {
;     ...
; #pragma unroll
;       for (int s2 = 0; s2 < 2; ++s2) {
;         const bf16x8 pb0 = pack8(pt[0], s2), pb1 = pack8(pt[1], s2);
;         const int s16 = 2 * ks + s2;
; #pragma unroll
;         for (int b = 0; b < 2; ++b) {
;           const char* va = base + KB + b * 4096 + s16 * 1024 + trofs;
;           const bf16x8 vf = cat8(vtr(va), vtr(va + 512));
;           o[0][b] = MFMA(vf, pb0, o[0][b]);
;           o[1][b] = MFMA(vf, pb1, o[1][b]);
;         }
;       }
;     ...
;     A_STORE(kA, vA, 1);
;     __syncthreads();
;     if (it + 2 < ntiles) A_LOAD(kA, vA, it + 2);
;     compute(lds + STAGE, it + 1);
;     if (it + 2 < ntiles) A_STORE(kA, vA, 0);
;     __syncthreads();
.LBB0_178:
	ds_read_b64_tr_b16 v[226:227], v185 offset:26624
	ds_read_b64_tr_b16 v[228:229], v185 offset:27136
	ds_read_b64_tr_b16 v[238:239], v185 offset:30720
	ds_read_b64_tr_b16 v[240:241], v185 offset:31232
	ds_read_b64_tr_b16 v[242:243], v185 offset:27648
	ds_read_b64_tr_b16 v[244:245], v185 offset:28160
	ds_read_b64_tr_b16 v[246:247], v185 offset:31744
	ds_read_b64_tr_b16 v[248:249], v185 offset:32256
	v_cvt_pk_bf16_f32 v0, v0, v1
	v_cvt_pk_bf16_f32 v1, v2, v3
	v_cvt_pk_bf16_f32 v2, v4, v5
	v_cvt_pk_bf16_f32 v3, v6, v7
	v_cvt_pk_bf16_f32 v4, v16, v17
	v_cvt_pk_bf16_f32 v5, v18, v19
	v_cvt_pk_bf16_f32 v6, v20, v21
	v_cvt_pk_bf16_f32 v7, v22, v23
	s_waitcnt lgkmcnt(6)
	v_mfma_f32_32x32x16_bf16 v[114:129], v[226:229], v[0:3], v[114:129]
	v_mfma_f32_32x32x16_bf16 v[82:97], v[226:229], v[4:7], v[82:97]
	s_waitcnt lgkmcnt(4)
	v_mfma_f32_32x32x16_bf16 v[98:113], v[238:241], v[0:3], v[98:113]
	v_cvt_pk_bf16_f32 v0, v8, v9
	v_cvt_pk_bf16_f32 v1, v10, v11
	v_cvt_pk_bf16_f32 v2, v12, v13
	v_cvt_pk_bf16_f32 v3, v14, v15
	v_exp_f32_e32 v63, v224
	s_andn2_b64 vcc, exec, s[44:45]
	v_mfma_f32_32x32x16_bf16 v[66:81], v[238:241], v[4:7], v[66:81]
	v_cvt_pk_bf16_f32 v4, v24, v25
	v_cvt_pk_bf16_f32 v5, v26, v27
	v_cvt_pk_bf16_f32 v6, v28, v29
	v_cvt_pk_bf16_f32 v7, v30, v63
	s_waitcnt lgkmcnt(2)
	v_mfma_f32_32x32x16_bf16 v[114:129], v[242:245], v[0:3], v[114:129]
	v_mfma_f32_32x32x16_bf16 v[82:97], v[242:245], v[4:7], v[82:97]
	s_waitcnt lgkmcnt(0)
	v_mfma_f32_32x32x16_bf16 v[98:113], v[246:249], v[0:3], v[98:113]
	v_mfma_f32_32x32x16_bf16 v[66:81], v[246:249], v[4:7], v[66:81]
	s_cbranch_vccnz .LBB0_127
	s_waitcnt vmcnt(3)
	ds_write_b128 v181, v[162:165]
	s_waitcnt vmcnt(1)
	ds_write_b128 v182, v[170:173]
	ds_write_b128 v219, v[166:169] offset:8192
	s_waitcnt vmcnt(0)
	ds_write_b128 v219, v[174:177] offset:10240
	s_branch .LBB0_127
